# IDX score loop: seven of the eight 64-bit multiply-adds that form the KI tile load addresses replaced by 64-bit adds of the constant row stride
# speedup vs baseline: 1.0055x; 1.0055x over previous
; #define LAS __attribute__((address_space(3)))
; #define LDS_WAIT() asm volatile("s_waitcnt lgkmcnt(0)" ::: "memory")
; __device__ __forceinline__ void idx_unit(bf16* QB, float* SC, int* SEL, const float* qg, const float* kg, int b, int tp, LAS unsigned char* wl, int lane, bool do_norm) {
;     ...
;         for (int s0 = 0; s0 < ce; s0 += 64) {
; #pragma unroll
;             for (int i = 0; i < 8; ++i) *(LAS bf16x8*)(sdst + (8 * i) * 144) = cur[i];
;             const int sn = (s0 + 64 < ce) ? s0 + 64 : 0;
; #pragma unroll
;             for (int i = 0; i < 8; ++i) cur[i] = *(const bf16x8*)(kg8 + (size_t)(sn + 8 * i) * NBP);
;             LDS_WAIT();
; #pragma unroll
;             for (int tt = 0; tt < 2; ++tt) {
;                 f32x16 acc0, acc1;
; #pragma unroll
;                 for (int r = 0; r < 16; ++r) { acc0[r] = 0.f; acc1[r] = 0.f; }
; #pragma unroll
;                 for (int ks = 0; ks < 4; ++ks) { const bf16x8 bfr = *(const LAS bf16x8*)(fsrc + tt * 32 * 144 + 32 * ks);
;                     acc0 = __builtin_amdgcn_mfma_f32_32x32x16_bf16(af[0][ks], bfr, acc0, 0, 0, 0); acc1 = __builtin_amdgcn_mfma_f32_32x32x16_bf16(af[1][ks], bfr, acc1, 0, 0, 0); }
;                 float pa = 0.f, pb = 0.f, pc = 0.f, pd = 0.f;
; #pragma unroll
;                 for (int r = 0; r < 8; ++r) { pa += w[0][r] * (__builtin_fmaxf(acc0[r], 0.f) * 0.125f); pb += w[1][r] * (__builtin_fmaxf(acc0[8 + r], 0.f) * 0.125f);
;                                               pc += w[2][r] * (__builtin_fmaxf(acc1[r], 0.f) * 0.125f); pd += w[3][r] * (__builtin_fmaxf(acc1[8 + r], 0.f) * 0.125f); }
;                 const float snd0 = hi ? pa : pb, snd1 = hi ? pc : pd; const float rcv0 = __shfl_xor(snd0, 32), rcv1 = __shfl_xor(snd1, 32);
;                 scw0[s0 + 32 * tt] = (hi ? pb : pa) + rcv0;
;                 scw1[s0 + 32 * tt] = (hi ? pd : pc) + rcv1;
.LBB0_243:
	s_add_i32 s3, s0, 64
	s_cmp_lt_i32 s0, s7
	s_cselect_b64 s[0:1], -1, 0
	s_and_b64 vcc, s[0:1], exec
	s_cselect_b32 s4, s3, 0
	v_mad_u64_u32 v[0:1], s[0:1], s4, v212, v[132:133]
	s_mov_b64 s[0:1], 0x11000
	s_waitcnt vmcnt(0)
	ds_write_b128 v101, v[64:67]
	ds_write_b128 v101, v[72:75] offset:1152
	ds_write_b128 v101, v[68:71] offset:2304
	ds_write_b128 v101, v[80:83] offset:3456
	ds_write_b128 v101, v[76:79] offset:4608
	ds_write_b128 v101, v[88:91] offset:5760
	ds_write_b128 v101, v[84:87] offset:6912
	ds_write_b128 v101, v[92:95] offset:8064
	global_load_dwordx4 v[64:67], v[0:1], off
	v_lshl_add_u64 v[0:1], v[0:1], 0, s[0:1]
	global_load_dwordx4 v[72:75], v[0:1], off
	v_lshl_add_u64 v[0:1], v[0:1], 0, s[0:1]
	global_load_dwordx4 v[68:71], v[0:1], off
	v_lshl_add_u64 v[0:1], v[0:1], 0, s[0:1]
	global_load_dwordx4 v[80:83], v[0:1], off
	v_lshl_add_u64 v[0:1], v[0:1], 0, s[0:1]
	global_load_dwordx4 v[76:79], v[0:1], off
	v_lshl_add_u64 v[0:1], v[0:1], 0, s[0:1]
	global_load_dwordx4 v[88:91], v[0:1], off
	v_lshl_add_u64 v[0:1], v[0:1], 0, s[0:1]
	global_load_dwordx4 v[84:87], v[0:1], off
	v_lshl_add_u64 v[0:1], v[0:1], 0, s[0:1]
	global_load_dwordx4 v[92:95], v[0:1], off
	s_waitcnt lgkmcnt(0)
	ds_read_b128 v[138:141], v103
	ds_read_b128 v[142:145], v103 offset:32
	ds_read_b128 v[146:149], v103 offset:64
	ds_read_b128 v[150:153], v103 offset:96
	s_waitcnt lgkmcnt(3)
	v_mfma_f32_32x32x16_bf16 v[16:31], v[40:43], v[138:141], 0
	v_add_co_u32_e64 v136, s[0:1], s5, v134
	s_nop 1
	v_addc_co_u32_e64 v137, s[0:1], 0, v135, s[0:1]
	s_mov_b64 s[0:1], 0x100
	v_mfma_f32_32x32x16_bf16 v[0:15], v[56:59], v[138:141], 0
	s_waitcnt lgkmcnt(2)
	v_mfma_f32_32x32x16_bf16 v[0:15], v[48:51], v[142:145], v[0:15]
	v_mfma_f32_32x32x16_bf16 v[16:31], v[32:35], v[142:145], v[16:31]
	s_waitcnt lgkmcnt(1)
	v_mfma_f32_32x32x16_bf16 v[0:15], v[52:55], v[146:149], v[0:15]
	v_mfma_f32_32x32x16_bf16 v[16:31], v[36:39], v[146:149], v[16:31]
	s_waitcnt lgkmcnt(0)
	v_mfma_f32_32x32x16_bf16 v[0:15], v[60:63], v[150:153], v[0:15]
	v_mfma_f32_32x32x16_bf16 v[16:31], v[44:47], v[150:153], v[16:31]
	ds_read_b128 v[154:157], v103 offset:4608
	ds_read_b128 v[158:161], v103 offset:4640
	ds_read_b128 v[162:165], v103 offset:4672
	ds_read_b128 v[166:169], v103 offset:4704
	s_nop 10
	v_max_f32_e32 v0, 0, v0
	v_max_f32_e32 v1, 0, v1
	v_fma_f32 v0, v232, v0, 0
	v_max_f32_e32 v8, 0, v8
	v_fmac_f32_e32 v0, v233, v1
	v_max_f32_e32 v1, 0, v9
	v_max_f32_e32 v16, 0, v16
	v_fma_f32 v8, v240, v8, 0
	v_max_f32_e32 v17, 0, v17
	v_fmac_f32_e32 v8, v241, v1
	v_fma_f32 v16, v131, v16, 0
	v_max_f32_e32 v1, 0, v18
	v_max_f32_e32 v24, 0, v24
	v_fmac_f32_e32 v16, v217, v17
	v_max_f32_e32 v17, 0, v25
	v_fmac_f32_e32 v16, v218, v1
	v_fma_f32 v24, v224, v24, 0
	v_max_f32_e32 v1, 0, v26
	v_fmac_f32_e32 v24, v225, v17
	v_fmac_f32_e32 v24, v226, v1
	v_max_f32_e32 v1, 0, v2
	v_fmac_f32_e32 v0, v234, v1
	v_max_f32_e32 v1, 0, v10
	v_fmac_f32_e32 v8, v242, v1
	v_max_f32_e32 v1, 0, v19
	v_fmac_f32_e32 v16, v219, v1
	v_max_f32_e32 v1, 0, v27
	v_fmac_f32_e32 v24, v227, v1
	v_max_f32_e32 v1, 0, v3
	v_fmac_f32_e32 v0, v235, v1
	v_max_f32_e32 v1, 0, v11
	v_fmac_f32_e32 v8, v243, v1
	v_max_f32_e32 v1, 0, v20
	v_fmac_f32_e32 v16, v220, v1
	v_max_f32_e32 v1, 0, v28
	v_fmac_f32_e32 v24, v228, v1
	v_max_f32_e32 v1, 0, v4
	v_fmac_f32_e32 v0, v236, v1
	v_max_f32_e32 v1, 0, v12
	v_fmac_f32_e32 v8, v244, v1
	v_max_f32_e32 v1, 0, v21
	v_fmac_f32_e32 v16, v221, v1
	v_max_f32_e32 v1, 0, v29
	v_fmac_f32_e32 v24, v229, v1
	v_max_f32_e32 v1, 0, v5
	v_fmac_f32_e32 v0, v237, v1
	v_max_f32_e32 v1, 0, v13
	v_fmac_f32_e32 v8, v245, v1
	v_max_f32_e32 v1, 0, v22
	v_fmac_f32_e32 v16, v222, v1
	v_max_f32_e32 v1, 0, v30
	v_fmac_f32_e32 v24, v230, v1
	v_max_f32_e32 v1, 0, v6
	v_fmac_f32_e32 v0, v238, v1
	v_max_f32_e32 v1, 0, v14
	v_fmac_f32_e32 v8, v246, v1
	v_max_f32_e32 v1, 0, v23
	v_fmac_f32_e32 v16, v223, v1
	v_max_f32_e32 v1, 0, v31
	v_fmac_f32_e32 v24, v231, v1
	v_max_f32_e32 v1, 0, v7
	v_fmac_f32_e32 v0, v239, v1
	v_max_f32_e32 v1, 0, v15
	v_fmac_f32_e32 v8, v247, v1
	v_cndmask_b32_e64 v1, v16, v24, s[40:41]
	v_cndmask_b32_e64 v2, v0, v8, s[40:41]
	ds_bpermute_b32 v1, v97, v1
	ds_bpermute_b32 v2, v97, v2
	v_cndmask_b32_e64 v3, v24, v16, s[40:41]
	v_cndmask_b32_e64 v0, v8, v0, s[40:41]
	s_waitcnt lgkmcnt(1)
	v_add_f32_e32 v1, v3, v1
	s_waitcnt lgkmcnt(0)
; #define LAS __attribute__((address_space(3)))
; #define LDS_WAIT() asm volatile("s_waitcnt lgkmcnt(0)" ::: "memory")
; __device__ __forceinline__ void select_query(const float* sc, int* sel, int ce, int lane) {
;     const int nreg = ce >> 6;
;     unsigned key[64];
;     {
;         float raw[64];
; #pragma unroll
;         for (int g = 0; g < 8; ++g) {
;             if (8 * g < nreg) {
; #pragma unroll
;                 for (int j = 8 * g; j < 8 * g + 8; ++j) raw[j] = sc[lane + 64 * j];
;             } else {
; #pragma unroll
;                 for (int j = 8 * g; j < 8 * g + 8; ++j) raw[j] = 0.f;
;             }
;         }
; #pragma unroll
;         for (int j = 0; j < 64; ++j) key[j] = (j < nreg) ? fkey(raw[j]) : 0u;
; __device__ __forceinline__ void idx_unit(bf16* QB, float* SC, int* SEL, const float* qg, const float* kg, int b, int tp, LAS unsigned char* wl, int lane, bool do_norm) {
;     ...
;             for (int tt = 0; tt < 2; ++tt) {
;                 f32x16 acc0, acc1;
; #pragma unroll
;                 for (int r = 0; r < 16; ++r) { acc0[r] = 0.f; acc1[r] = 0.f; }
; #pragma unroll
;                 for (int ks = 0; ks < 4; ++ks) { const bf16x8 bfr = *(const LAS bf16x8*)(fsrc + tt * 32 * 144 + 32 * ks);
;                     acc0 = __builtin_amdgcn_mfma_f32_32x32x16_bf16(af[0][ks], bfr, acc0, 0, 0, 0); acc1 = __builtin_amdgcn_mfma_f32_32x32x16_bf16(af[1][ks], bfr, acc1, 0, 0, 0); }
;                 float pa = 0.f, pb = 0.f, pc = 0.f, pd = 0.f;
; #pragma unroll
;                 for (int r = 0; r < 8; ++r) { pa += w[0][r] * (__builtin_fmaxf(acc0[r], 0.f) * 0.125f); pb += w[1][r] * (__builtin_fmaxf(acc0[8 + r], 0.f) * 0.125f);
;                                               pc += w[2][r] * (__builtin_fmaxf(acc1[r], 0.f) * 0.125f); pd += w[3][r] * (__builtin_fmaxf(acc1[8 + r], 0.f) * 0.125f); }
;                 const float snd0 = hi ? pa : pb, snd1 = hi ? pc : pd; const float rcv0 = __shfl_xor(snd0, 32), rcv1 = __shfl_xor(snd1, 32);
;                 scw0[s0 + 32 * tt] = (hi ? pb : pa) + rcv0;
;                 scw1[s0 + 32 * tt] = (hi ? pd : pc) + rcv1;
;             }
;             LDS_WAIT();
;         }
;         __builtin_amdgcn_fence(__ATOMIC_SEQ_CST, "workgroup");
;         asm volatile("s_waitcnt vmcnt(0)" ::: "memory");
; #pragma unroll 1
;         for (int a = 0; a < 4; ++a) select_query(SC + (row + a) * SEQ, SEL + (row + a) * 256, ce, lane);
	v_add_f32_e32 v0, v0, v2
	global_store_dword v[134:135], v1, off
	global_store_dword v[136:137], v0, off
	v_mfma_f32_32x32x16_bf16 v[16:31], v[40:43], v[154:157], 0
	v_mfma_f32_32x32x16_bf16 v[0:15], v[56:59], v[154:157], 0
	v_mfma_f32_32x32x16_bf16 v[0:15], v[48:51], v[158:161], v[0:15]
	v_mfma_f32_32x32x16_bf16 v[16:31], v[32:35], v[158:161], v[16:31]
	v_mfma_f32_32x32x16_bf16 v[0:15], v[52:55], v[162:165], v[0:15]
	v_mfma_f32_32x32x16_bf16 v[16:31], v[36:39], v[162:165], v[16:31]
	v_mfma_f32_32x32x16_bf16 v[0:15], v[60:63], v[166:169], v[0:15]
	v_mfma_f32_32x32x16_bf16 v[16:31], v[44:47], v[166:169], v[16:31]
	s_nop 10
	v_max_f32_e32 v0, 0, v0
	v_max_f32_e32 v1, 0, v1
	v_fma_f32 v0, v232, v0, 0
	v_max_f32_e32 v8, 0, v8
	v_fmac_f32_e32 v0, v233, v1
	v_max_f32_e32 v1, 0, v9
	v_max_f32_e32 v16, 0, v16
	v_fma_f32 v8, v240, v8, 0
	v_max_f32_e32 v17, 0, v17
	v_fmac_f32_e32 v8, v241, v1
	v_fma_f32 v16, v131, v16, 0
	v_max_f32_e32 v1, 0, v18
	v_max_f32_e32 v24, 0, v24
	v_fmac_f32_e32 v16, v217, v17
	v_max_f32_e32 v17, 0, v25
	v_fmac_f32_e32 v16, v218, v1
	v_fma_f32 v24, v224, v24, 0
	v_max_f32_e32 v1, 0, v26
	v_fmac_f32_e32 v24, v225, v17
	v_fmac_f32_e32 v24, v226, v1
	v_max_f32_e32 v1, 0, v2
	v_fmac_f32_e32 v0, v234, v1
	v_max_f32_e32 v1, 0, v10
	v_fmac_f32_e32 v8, v242, v1
	v_max_f32_e32 v1, 0, v19
	v_fmac_f32_e32 v16, v219, v1
	v_max_f32_e32 v1, 0, v27
	v_fmac_f32_e32 v24, v227, v1
	v_max_f32_e32 v1, 0, v3
	v_fmac_f32_e32 v0, v235, v1
	v_max_f32_e32 v1, 0, v11
	v_fmac_f32_e32 v8, v243, v1
	v_max_f32_e32 v1, 0, v20
	v_fmac_f32_e32 v16, v220, v1
	v_max_f32_e32 v1, 0, v28
	v_fmac_f32_e32 v24, v228, v1
	v_max_f32_e32 v1, 0, v4
	v_fmac_f32_e32 v0, v236, v1
	v_max_f32_e32 v1, 0, v12
	v_fmac_f32_e32 v8, v244, v1
	v_max_f32_e32 v1, 0, v21
	v_fmac_f32_e32 v16, v221, v1
	v_max_f32_e32 v1, 0, v29
	v_fmac_f32_e32 v24, v229, v1
	v_max_f32_e32 v1, 0, v5
	v_fmac_f32_e32 v0, v237, v1
	v_max_f32_e32 v1, 0, v13
	v_fmac_f32_e32 v8, v245, v1
	v_max_f32_e32 v1, 0, v22
	v_fmac_f32_e32 v16, v222, v1
	v_max_f32_e32 v1, 0, v30
	v_fmac_f32_e32 v24, v230, v1
	v_max_f32_e32 v1, 0, v6
	v_fmac_f32_e32 v0, v238, v1
	v_max_f32_e32 v1, 0, v14
	v_fmac_f32_e32 v8, v246, v1
	v_max_f32_e32 v1, 0, v23
	v_fmac_f32_e32 v16, v223, v1
	v_max_f32_e32 v1, 0, v31
	v_fmac_f32_e32 v24, v231, v1
	v_max_f32_e32 v1, 0, v7
	v_fmac_f32_e32 v0, v239, v1
	v_max_f32_e32 v1, 0, v15
	v_fmac_f32_e32 v8, v247, v1
	v_cndmask_b32_e64 v1, v16, v24, s[40:41]
	v_cndmask_b32_e64 v2, v0, v8, s[40:41]
	ds_bpermute_b32 v1, v97, v1
	ds_bpermute_b32 v2, v97, v2
	v_cndmask_b32_e64 v3, v24, v16, s[40:41]
	v_cndmask_b32_e64 v0, v8, v0, s[40:41]
	s_waitcnt lgkmcnt(1)
	v_add_f32_e32 v1, v3, v1
	s_waitcnt lgkmcnt(0)
	v_add_f32_e32 v0, v0, v2
	global_store_dword v[134:135], v1, off offset:128
	global_store_dword v[136:137], v0, off offset:128
	s_waitcnt lgkmcnt(0)
	v_lshl_add_u64 v[134:135], v[134:135], 0, s[0:1]
	s_mov_b32 s0, s3
	s_cbranch_vccnz .LBB0_243
	v_add_u32_e32 v138, 0x180, v96
	v_add_u32_e32 v139, 0x1c0, v96
	v_add_u32_e32 v140, 0x200, v96
	v_add_u32_e32 v141, 0x240, v96
	v_add_u32_e32 v142, 0x280, v96
	v_add_u32_e32 v143, 0x2c0, v96
	v_add_u32_e32 v144, 0x300, v96
	v_add_u32_e32 v145, 0x340, v96
	v_add_u32_e32 v146, 0x380, v96
	v_add_u32_e32 v147, 0x3c0, v96
	v_add_u32_e32 v148, 0x400, v96
	v_add_u32_e32 v149, 0x440, v96
	v_add_u32_e32 v150, 0x480, v96
	v_add_u32_e32 v151, 0x4c0, v96
	v_add_u32_e32 v152, 0x500, v96
	v_add_u32_e32 v153, 0x540, v96
	v_add_u32_e32 v154, 0x580, v96
	v_add_u32_e32 v155, 0x5c0, v96
	v_add_u32_e32 v156, 0x600, v96
	v_add_u32_e32 v157, 0x640, v96
	v_add_u32_e32 v158, 0x680, v96
	v_add_u32_e32 v159, 0x6c0, v96
	v_add_u32_e32 v160, 0x700, v96
	v_add_u32_e32 v161, 0x740, v96
	v_add_u32_e32 v162, 0x780, v96
	v_add_u32_e32 v163, 0x7c0, v96
	v_add_u32_e32 v164, 0x800, v96
	v_add_u32_e32 v165, 0x840, v96
	v_add_u32_e32 v166, 0x880, v96
	v_add_u32_e32 v167, 0x8c0, v96
	v_add_u32_e32 v168, 0x900, v96
	v_add_u32_e32 v169, 0x940, v96
	s_cmpk_gt_u32 s6, 0x23f
	s_cselect_b64 s[84:85], -1, 0
	s_cmpk_gt_u32 s6, 0x43f
	s_cselect_b64 s[86:87], -1, 0
	s_cmpk_gt_u32 s6, 0x63f
	s_cselect_b64 s[88:89], -1, 0
	s_cmpk_gt_u32 s6, 0x83f
	s_cselect_b64 s[90:91], -1, 0
	s_cmpk_gt_u32 s6, 0xa3f
	s_cselect_b64 s[92:93], -1, 0
	s_cmpk_gt_u32 s6, 0xc3f
	s_cselect_b64 s[94:95], -1, 0
	s_cmpk_gt_u32 s6, 0xe3f
	s_cselect_b64 s[96:97], -1, 0
	s_cmpk_gt_u32 s6, 0x17f
	s_cselect_b64 s[0:1], -1, 0
	v_writelane_b32 v254, s0, 7
	s_cmpk_gt_u32 s6, 0x1bf
	s_nop 0
	v_writelane_b32 v254, s1, 8
	s_cselect_b64 s[0:1], -1, 0
	v_writelane_b32 v254, s0, 9
	s_cmpk_gt_u32 s6, 0x1ff
	s_waitcnt vmcnt(0)
; __device__ __forceinline__ unsigned fkey(float f) { const unsigned u = __builtin_bit_cast(unsigned, f); return (u & 0x80000000u) ? ~u : (u | 0x80000000u); }
; __device__ __forceinline__ void select_query(const float* sc, int* sel, int ce, int lane) {
;     const int nreg = ce >> 6;
;     unsigned key[64];
;     {
;         float raw[64];
; #pragma unroll
;         for (int g = 0; g < 8; ++g) {
;             if (8 * g < nreg) {
; #pragma unroll
;                 for (int j = 8 * g; j < 8 * g + 8; ++j) raw[j] = sc[lane + 64 * j];
;             } else {
; #pragma unroll
;                 for (int j = 8 * g; j < 8 * g + 8; ++j) raw[j] = 0.f;
;             }
;         }
; #pragma unroll
;         for (int j = 0; j < 64; ++j) key[j] = (j < nreg) ? fkey(raw[j]) : 0u;
	s_mov_b32 s3, 0
	v_writelane_b32 v254, s1, 10
	s_cselect_b64 s[0:1], -1, 0
	v_writelane_b32 v254, s0, 11
	s_cmpk_gt_u32 s6, 0x27f
	s_nop 0
	v_writelane_b32 v254, s1, 12
	s_cselect_b64 s[0:1], -1, 0
	v_writelane_b32 v254, s0, 13
	s_cmpk_gt_u32 s6, 0x2bf
	s_nop 0
	v_writelane_b32 v254, s1, 14
	s_cselect_b64 s[0:1], -1, 0
	v_writelane_b32 v254, s0, 15
	s_cmpk_gt_u32 s6, 0x2ff
	s_nop 0
	v_writelane_b32 v254, s1, 16
	s_cselect_b64 s[0:1], -1, 0
	v_writelane_b32 v254, s0, 17
	s_cmpk_gt_u32 s6, 0x33f
	s_nop 0
	v_writelane_b32 v254, s1, 18
	s_cselect_b64 s[0:1], -1, 0
	v_writelane_b32 v254, s0, 19
	s_cmpk_gt_u32 s6, 0x37f
	s_nop 0
	v_writelane_b32 v254, s1, 20
	s_cselect_b64 s[0:1], -1, 0
	v_writelane_b32 v254, s0, 21
	s_cmpk_gt_u32 s6, 0x3bf
	s_nop 0
	v_writelane_b32 v254, s1, 22
	s_cselect_b64 s[0:1], -1, 0
	v_writelane_b32 v254, s0, 23
	s_cmpk_gt_u32 s6, 0x3ff
	s_nop 0
	v_writelane_b32 v254, s1, 24
	s_cselect_b64 s[0:1], -1, 0
	v_writelane_b32 v254, s0, 25
	s_cmpk_gt_u32 s6, 0x47f
	s_nop 0
	v_writelane_b32 v254, s1, 26
	s_cselect_b64 s[0:1], -1, 0
	v_writelane_b32 v254, s0, 27
	s_cmpk_gt_u32 s6, 0x4bf
	s_nop 0
	v_writelane_b32 v254, s1, 28
	s_cselect_b64 s[0:1], -1, 0
	v_writelane_b32 v254, s0, 29
	s_cmpk_gt_u32 s6, 0x4ff
	s_nop 0
	v_writelane_b32 v254, s1, 30
	s_cselect_b64 s[0:1], -1, 0
	v_writelane_b32 v254, s0, 31
	s_cmpk_gt_u32 s6, 0x53f
	s_nop 0
	v_writelane_b32 v254, s1, 32
	s_cselect_b64 s[0:1], -1, 0
	v_writelane_b32 v254, s0, 33
	s_cmpk_gt_u32 s6, 0x57f
	s_nop 0
	v_writelane_b32 v254, s1, 34
	s_cselect_b64 s[0:1], -1, 0
	v_writelane_b32 v254, s0, 35
	s_cmpk_gt_u32 s6, 0x5bf
	s_nop 0
	v_writelane_b32 v254, s1, 36
	s_cselect_b64 s[0:1], -1, 0
	v_writelane_b32 v254, s0, 37
	s_cmpk_gt_u32 s6, 0x5ff
	s_nop 0
	v_writelane_b32 v254, s1, 38
	s_cselect_b64 s[0:1], -1, 0
	v_writelane_b32 v254, s0, 39
	s_cmpk_gt_u32 s6, 0x67f
	s_nop 0
	v_writelane_b32 v254, s1, 40
	s_cselect_b64 s[0:1], -1, 0
	v_writelane_b32 v254, s0, 41
	s_cmpk_gt_u32 s6, 0x6bf
	s_nop 0
	v_writelane_b32 v254, s1, 42
	s_cselect_b64 s[0:1], -1, 0
	v_writelane_b32 v254, s0, 43
	s_cmpk_gt_u32 s6, 0x6ff
	s_nop 0
	v_writelane_b32 v254, s1, 44
	s_cselect_b64 s[0:1], -1, 0
	v_writelane_b32 v254, s0, 45
	s_cmpk_gt_u32 s6, 0x73f
	s_nop 0
	v_writelane_b32 v254, s1, 46
	s_cselect_b64 s[0:1], -1, 0
	v_writelane_b32 v254, s0, 47
	s_cmpk_gt_u32 s6, 0x77f
	s_nop 0
	v_writelane_b32 v254, s1, 48
	s_cselect_b64 s[0:1], -1, 0
	v_writelane_b32 v254, s0, 49
	s_cmpk_gt_u32 s6, 0x7bf
	s_nop 0
	v_writelane_b32 v254, s1, 50
	s_cselect_b64 s[0:1], -1, 0
	v_writelane_b32 v254, s0, 51
	s_cmpk_gt_u32 s6, 0x7ff
	s_nop 0
	v_writelane_b32 v254, s1, 52
	s_cselect_b64 s[0:1], -1, 0
	v_writelane_b32 v254, s0, 53
	s_cmpk_gt_u32 s6, 0x87f
	s_nop 0
	v_writelane_b32 v254, s1, 54
	s_cselect_b64 s[0:1], -1, 0
	v_writelane_b32 v254, s0, 55
	s_cmpk_gt_u32 s6, 0x8bf
	s_nop 0
	v_writelane_b32 v254, s1, 56
	s_cselect_b64 s[0:1], -1, 0
	v_writelane_b32 v254, s0, 57
	s_cmpk_gt_u32 s6, 0x8ff
	s_nop 0
	v_writelane_b32 v254, s1, 58
	s_cselect_b64 s[0:1], -1, 0
	v_writelane_b32 v254, s0, 59
	s_cmpk_gt_u32 s6, 0x93f
	s_nop 0
	v_writelane_b32 v254, s1, 60
	s_cselect_b64 s[0:1], -1, 0
	v_writelane_b32 v254, s0, 61
	s_cmpk_gt_u32 s6, 0x97f
	s_nop 0
	v_writelane_b32 v254, s1, 62
	s_cselect_b64 s[0:1], -1, 0
	v_writelane_b32 v254, s0, 63
	s_cmpk_gt_u32 s6, 0x9bf
	s_nop 0
	v_writelane_b32 v250, s1, 0
	s_cselect_b64 s[0:1], -1, 0
	v_writelane_b32 v250, s0, 1
	s_cmpk_gt_u32 s6, 0x9ff
	s_nop 0
	v_writelane_b32 v250, s1, 2
	s_cselect_b64 s[0:1], -1, 0
	v_writelane_b32 v250, s0, 3
	s_cmpk_gt_u32 s6, 0xa7f
	s_nop 0
	v_writelane_b32 v250, s1, 4
	s_cselect_b64 s[0:1], -1, 0
	v_writelane_b32 v250, s0, 5
	s_cmpk_gt_u32 s6, 0xabf
	s_nop 0
	v_writelane_b32 v250, s1, 6
	s_cselect_b64 s[0:1], -1, 0
	v_writelane_b32 v250, s0, 7
	s_cmpk_gt_u32 s6, 0xaff
	s_nop 0
	v_writelane_b32 v250, s1, 8
	s_cselect_b64 s[0:1], -1, 0
	v_writelane_b32 v250, s0, 9
	s_cmpk_gt_u32 s6, 0xb3f
	s_nop 0
	v_writelane_b32 v250, s1, 10
	s_cselect_b64 s[0:1], -1, 0
	v_writelane_b32 v250, s0, 11
	s_cmpk_gt_u32 s6, 0xb7f
	s_nop 0
	v_writelane_b32 v250, s1, 12
	s_cselect_b64 s[0:1], -1, 0
	v_writelane_b32 v250, s0, 13
	s_cmpk_gt_u32 s6, 0xbbf
	s_nop 0
	v_writelane_b32 v250, s1, 14
	s_cselect_b64 s[0:1], -1, 0
	v_writelane_b32 v250, s0, 15
	s_cmpk_gt_u32 s6, 0xbff
	s_nop 0
	v_writelane_b32 v250, s1, 16
	s_cselect_b64 s[0:1], -1, 0
	v_writelane_b32 v250, s0, 17
	s_cmpk_gt_u32 s6, 0xc7f
	s_nop 0
	v_writelane_b32 v250, s1, 18
	s_cselect_b64 s[0:1], -1, 0
	v_writelane_b32 v250, s0, 19
	s_cmpk_gt_u32 s6, 0xcbf
	s_nop 0
	v_writelane_b32 v250, s1, 20
	s_cselect_b64 s[0:1], -1, 0
	v_writelane_b32 v250, s0, 21
	s_cmpk_gt_u32 s6, 0xcff
	s_nop 0
	v_writelane_b32 v250, s1, 22
	s_cselect_b64 s[0:1], -1, 0
	v_writelane_b32 v250, s0, 23
	s_cmpk_gt_u32 s6, 0xd3f
	s_nop 0
	v_writelane_b32 v250, s1, 24
	s_cselect_b64 s[0:1], -1, 0
	v_writelane_b32 v250, s0, 25
	s_cmpk_gt_u32 s6, 0xd7f
	s_nop 0
	v_writelane_b32 v250, s1, 26
	s_cselect_b64 s[0:1], -1, 0
	v_writelane_b32 v250, s0, 27
	s_cmpk_gt_u32 s6, 0xdbf
	s_nop 0
	v_writelane_b32 v250, s1, 28
	s_cselect_b64 s[0:1], -1, 0
	v_writelane_b32 v250, s0, 29
	s_cmpk_gt_u32 s6, 0xdff
	s_nop 0
	v_writelane_b32 v250, s1, 30
	s_cselect_b64 s[0:1], -1, 0
	s_cmpk_gt_u32 s6, 0xe7f
	s_cselect_b64 s[36:37], -1, 0
	s_cmpk_gt_u32 s6, 0xebf
	s_cselect_b64 s[38:39], -1, 0
	s_cmpk_gt_u32 s6, 0xeff
	s_cselect_b64 s[42:43], -1, 0
	s_cmpk_gt_u32 s6, 0xf3f
	s_cselect_b64 s[44:45], -1, 0
	s_cmpk_gt_u32 s6, 0xf7f
	s_cselect_b64 s[46:47], -1, 0
	s_cmpk_gt_u32 s6, 0xfbf
	s_cselect_b64 s[48:49], -1, 0
	s_cmpk_gt_u32 s6, 0xfff
	v_writelane_b32 v250, s0, 31
	s_cselect_b64 s[50:51], -1, 0
	s_nop 0
	v_writelane_b32 v250, s1, 32
	s_branch .LBB0_247
